# nt policy on WOUT/DOWN epilogue residual loads in addition to XN1 rows
# baseline (speedup 1.0000x reference)
;     __device__ __forceinline__ void operator()(const f32x4 (&acc)[2][2][4][2], const pg8::Unit& u, int wr, int wc, int fr, int fq) const {
;         const bool isc = u.pm == 64; const float* src = isc ? cin : hin; float* dst = isc ? cout : hout; const float* gv = isc ? gc : gl;
;         const int rbase = (isc ? 0 : u.pm * 256) + wr * 64 + fr, col0 = u.pn * 256 + wc * 32 + 4 * fq;
; #pragma unroll
;         for (int bj = 0; bj < 2; ++bj)
; #pragma unroll
;             for (int n = 0; n < 2; ++n) { const int col = col0 + bj * 128 + n * 16; const f32x4 g = *(const f32x4*)(gv + col); f32x4 h[2][4];
; #pragma unroll
;                 for (int ai = 0; ai < 2; ++ai)
; #pragma unroll
;                     for (int m = 0; m < 4; ++m) h[ai][m] = *(const f32x4*)(src + (size_t)(rbase + ai * 128 + m * 16) * DM + col);
; #pragma unroll
;                 for (int ai = 0; ai < 2; ++ai)
; #pragma unroll
;                     for (int m = 0; m < 4; ++m) *(f32x4*)(dst + (size_t)(rbase + ai * 128 + m * 16) * DM + col) = h[ai][m] + g * acc[ai][bj][m][n]; }
.LBB0_1258:
	s_lshl_b32 s11, s24, 8
	s_cmp_eq_u32 s24, 64
	s_cselect_b32 s11, 0, s11
	v_lshl_or_b32 v138, s22, 8, v172
	v_add_u32_e32 v136, s11, v170
	v_ashrrev_i32_e32 v139, 31, v138
	s_cselect_b32 s27, s54, s52
	s_cselect_b32 s26, s55, s53
	s_mov_b32 s15, 0x10000
	v_lshlrev_b64 v[138:139], 2, v[138:139]
	v_ashrrev_i32_e32 v137, 31, v136
	s_cselect_b32 s15, s15, 0x4000
	v_lshl_add_u64 v[140:141], s[26:27], 0, v[138:139]
	v_lshlrev_b64 v[142:143], 13, v[136:137]
	s_mov_b64 s[26:27], 0x100000
	s_cselect_b32 s39, s49, s17
	s_cselect_b32 s38, s48, s16
	s_add_u32 s40, s50, s15
	v_lshl_add_u64 v[156:157], v[142:143], 0, s[26:27]
	s_mov_b64 s[26:27], 0x120000
	s_addc_u32 s41, s51, 0
	v_or_b32_e32 v144, 16, v136
	v_or_b32_e32 v146, 32, v136
	v_lshl_add_u64 v[194:195], v[142:143], 0, s[26:27]
	s_mov_b64 s[26:27], 0x140000
	v_lshl_add_u64 v[148:149], s[40:41], 0, v[138:139]
	v_ashrrev_i32_e32 v145, 31, v144
	v_ashrrev_i32_e32 v147, 31, v146
	v_or_b32_e32 v136, 48, v136
	v_lshl_add_u64 v[218:219], v[142:143], 0, s[26:27]
	s_mov_b64 s[26:27], 0x160000
	global_load_dwordx4 v[174:177], v[148:149], off nt
	v_lshl_add_u64 v[152:153], v[140:141], 0, v[142:143]
	v_lshlrev_b64 v[144:145], 13, v[144:145]
	v_lshlrev_b64 v[146:147], 13, v[146:147]
	v_ashrrev_i32_e32 v137, 31, v136
	v_lshl_add_u64 v[220:221], v[142:143], 0, s[26:27]
	v_lshl_add_u64 v[154:155], v[140:141], 0, v[144:145]
	global_load_dwordx4 v[178:181], v[152:153], off nt
	global_load_dwordx4 v[182:185], v[154:155], off nt
	v_lshl_add_u64 v[158:159], v[140:141], 0, v[146:147]
	v_lshlrev_b64 v[150:151], 13, v[136:137]
	v_lshl_add_u64 v[162:163], v[140:141], 0, v[156:157]
	v_lshl_add_u64 v[166:167], v[140:141], 0, v[218:219]
	v_lshl_add_u64 v[168:169], v[140:141], 0, v[220:221]
	v_lshl_add_u64 v[160:161], v[140:141], 0, v[150:151]
	global_load_dwordx4 v[186:189], v[158:159], off nt
	global_load_dwordx4 v[190:193], v[160:161], off nt
	v_lshl_add_u64 v[164:165], v[140:141], 0, v[194:195]
	global_load_dwordx4 v[202:205], v[162:163], off nt
	global_load_dwordx4 v[206:209], v[164:165], off nt
	global_load_dwordx4 v[210:213], v[166:167], off nt
	global_load_dwordx4 v[214:217], v[168:169], off nt
	v_lshl_add_u64 v[230:231], s[38:39], 0, v[138:139]
	v_lshl_add_u64 v[136:137], v[230:231], 0, v[142:143]
	v_lshl_add_u64 v[138:139], v[230:231], 0, v[144:145]
	v_lshl_add_u64 v[140:141], v[230:231], 0, v[146:147]
	v_lshl_add_u64 v[142:143], v[230:231], 0, v[150:151]
	v_lshl_add_u64 v[144:145], v[230:231], 0, v[156:157]
	v_lshl_add_u64 v[146:147], v[230:231], 0, v[194:195]
	v_lshl_add_u64 v[150:151], v[230:231], 0, v[218:219]
	v_lshl_add_u64 v[156:157], v[230:231], 0, v[220:221]
	s_andn2_b64 vcc, exec, s[4:5]
	s_mov_b64 s[4:5], -1
	s_movk_i32 s62, 0x50
	s_mov_b32 s63, 0x8200
	s_movk_i32 s64, 0x63f
	s_movk_i32 s65, 0xdff
	s_waitcnt vmcnt(0)
	v_pk_fma_f32 v[100:101], v[100:101], v[176:177], v[180:181]
	v_pk_fma_f32 v[98:99], v[98:99], v[174:175], v[178:179]
	global_store_dwordx4 v[136:137], v[98:101], off
	s_nop 1
	v_pk_fma_f32 v[100:101], v[104:105], v[176:177], v[184:185]
	v_pk_fma_f32 v[98:99], v[102:103], v[174:175], v[182:183]
	v_pk_fma_f32 v[104:105], v[108:109], v[176:177], v[188:189]
	v_pk_fma_f32 v[102:103], v[106:107], v[174:175], v[186:187]
	v_pk_fma_f32 v[108:109], v[112:113], v[176:177], v[192:193]
	v_pk_fma_f32 v[106:107], v[110:111], v[174:175], v[190:191]
	v_pk_fma_f32 v[112:113], v[116:117], v[176:177], v[204:205]
	v_pk_fma_f32 v[110:111], v[114:115], v[174:175], v[202:203]
	v_pk_fma_f32 v[116:117], v[120:121], v[176:177], v[208:209]
	v_pk_fma_f32 v[114:115], v[118:119], v[174:175], v[206:207]
	v_pk_fma_f32 v[120:121], v[124:125], v[176:177], v[212:213]
	v_pk_fma_f32 v[118:119], v[122:123], v[174:175], v[210:211]
	v_pk_fma_f32 v[124:125], v[128:129], v[176:177], v[216:217]
	v_pk_fma_f32 v[122:123], v[126:127], v[174:175], v[214:215]
	global_store_dwordx4 v[138:139], v[98:101], off
	global_store_dwordx4 v[140:141], v[102:105], off
	global_store_dwordx4 v[142:143], v[106:109], off
	global_store_dwordx4 v[144:145], v[110:113], off
	global_store_dwordx4 v[146:147], v[114:117], off
	global_store_dwordx4 v[150:151], v[118:121], off
	global_store_dwordx4 v[156:157], v[122:125], off
	global_load_dwordx4 v[98:101], v[148:149], off offset:64 nt
	global_load_dwordx4 v[102:105], v[152:153], off offset:64 nt
	global_load_dwordx4 v[106:109], v[154:155], off offset:64 nt
	global_load_dwordx4 v[110:113], v[158:159], off offset:64 nt
	global_load_dwordx4 v[114:117], v[160:161], off offset:64 nt
	global_load_dwordx4 v[118:121], v[162:163], off offset:64 nt
	global_load_dwordx4 v[122:125], v[164:165], off offset:64 nt
	global_load_dwordx4 v[126:129], v[166:167], off offset:64 nt
	global_load_dwordx4 v[174:177], v[168:169], off offset:64 nt
	s_waitcnt vmcnt(7)
	v_pk_fma_f32 v[80:81], v[80:81], v[100:101], v[104:105]
	v_pk_fma_f32 v[78:79], v[78:79], v[98:99], v[102:103]
	s_waitcnt vmcnt(6)
	v_pk_fma_f32 v[76:77], v[76:77], v[100:101], v[108:109]
	v_pk_fma_f32 v[74:75], v[74:75], v[98:99], v[106:107]
	s_waitcnt vmcnt(5)
	v_pk_fma_f32 v[72:73], v[72:73], v[100:101], v[112:113]
	v_pk_fma_f32 v[70:71], v[70:71], v[98:99], v[110:111]
	s_waitcnt vmcnt(4)
	v_pk_fma_f32 v[68:69], v[68:69], v[100:101], v[116:117]
	v_pk_fma_f32 v[66:67], v[66:67], v[98:99], v[114:115]
	s_waitcnt vmcnt(3)
	v_pk_fma_f32 v[96:97], v[96:97], v[100:101], v[120:121]
	v_pk_fma_f32 v[94:95], v[94:95], v[98:99], v[118:119]
	s_waitcnt vmcnt(2)
	v_pk_fma_f32 v[92:93], v[92:93], v[100:101], v[124:125]
	v_pk_fma_f32 v[90:91], v[90:91], v[98:99], v[122:123]
	s_waitcnt vmcnt(1)
; #define PG8_BAR __builtin_amdgcn_s_barrier()
; template <class Epi, class Sched, bool ALIGN_EPI = false, bool SP2 = false>
; __device__ __forceinline__ void gemm_phase(PG8_LAS unsigned char* lds, const Gemm g, const Sched& S, const Epi& E) {
;     ...
; #pragma unroll
;         for (int a = 0; a < 2; ++a)
; #pragma unroll
;             for (int b = 0; b < 2; ++b)
; #pragma unroll
;                 for (int m = 0; m < 4; ++m)
; #pragma unroll
;                     for (int n = 0; n < 2; ++n) { float zr_ = 0.f; asm volatile("" : "+v"(zr_)); acc[a][b][m][n] = (f32x4){zr_, zr_, zr_, zr_}; }
;         cur = nxt; cA = nA; cB = nB; ++ui;
;         if constexpr (ALIGN_EPI) { if (wr == 1) PG8_BAR; }
;     __device__ __forceinline__ void operator()(const f32x4 (&acc)[2][2][4][2], const pg8::Unit& u, int wr, int wc, int fr, int fq) const {
;     ...
;             for (int n = 0; n < 2; ++n) { const int col = col0 + bj * 128 + n * 16; const f32x4 g = *(const f32x4*)(gv + col); f32x4 h[2][4];
; #pragma unroll
;                 for (int ai = 0; ai < 2; ++ai)
; #pragma unroll
;                     for (int m = 0; m < 4; ++m) h[ai][m] = *(const f32x4*)(src + (size_t)(rbase + ai * 128 + m * 16) * DM + col);
; #pragma unroll
;                 for (int ai = 0; ai < 2; ++ai)
; #pragma unroll
;                     for (int m = 0; m < 4; ++m) *(f32x4*)(dst + (size_t)(rbase + ai * 128 + m * 16) * DM + col) = h[ai][m] + g * acc[ai][bj][m][n]; }
	v_pk_fma_f32 v[88:89], v[88:89], v[100:101], v[128:129]
	v_pk_fma_f32 v[86:87], v[86:87], v[98:99], v[126:127]
	s_waitcnt vmcnt(0)
	v_pk_fma_f32 v[84:85], v[84:85], v[100:101], v[176:177]
	v_pk_fma_f32 v[82:83], v[82:83], v[98:99], v[174:175]
	global_store_dwordx4 v[136:137], v[78:81], off offset:64
	global_store_dwordx4 v[138:139], v[74:77], off offset:64
	global_store_dwordx4 v[140:141], v[70:73], off offset:64
	global_store_dwordx4 v[142:143], v[66:69], off offset:64
	global_store_dwordx4 v[144:145], v[94:97], off offset:64
	global_store_dwordx4 v[146:147], v[90:93], off offset:64
	global_store_dwordx4 v[150:151], v[86:89], off offset:64
	global_store_dwordx4 v[156:157], v[82:85], off offset:64
	global_load_dwordx4 v[66:69], v[148:149], off offset:512 nt
	global_load_dwordx4 v[70:73], v[152:153], off offset:512 nt
	global_load_dwordx4 v[74:77], v[154:155], off offset:512 nt
	global_load_dwordx4 v[78:81], v[158:159], off offset:512 nt
	s_nop 0
	global_load_dwordx4 v[82:85], v[160:161], off offset:512 nt
	global_load_dwordx4 v[86:89], v[162:163], off offset:512 nt
	global_load_dwordx4 v[90:93], v[164:165], off offset:512 nt
	global_load_dwordx4 v[94:97], v[166:167], off offset:512 nt
	global_load_dwordx4 v[98:101], v[168:169], off offset:512 nt
	s_waitcnt vmcnt(7)
	v_pk_fma_f32 v[48:49], v[48:49], v[68:69], v[72:73]
	v_pk_fma_f32 v[46:47], v[46:47], v[66:67], v[70:71]
	s_waitcnt vmcnt(6)
	v_pk_fma_f32 v[44:45], v[44:45], v[68:69], v[76:77]
	v_pk_fma_f32 v[42:43], v[42:43], v[66:67], v[74:75]
	s_waitcnt vmcnt(5)
	v_pk_fma_f32 v[40:41], v[40:41], v[68:69], v[80:81]
	v_pk_fma_f32 v[38:39], v[38:39], v[66:67], v[78:79]
	s_waitcnt vmcnt(4)
	v_pk_fma_f32 v[36:37], v[36:37], v[68:69], v[84:85]
	v_pk_fma_f32 v[34:35], v[34:35], v[66:67], v[82:83]
	s_waitcnt vmcnt(3)
	v_pk_fma_f32 v[64:65], v[64:65], v[68:69], v[88:89]
	v_pk_fma_f32 v[62:63], v[62:63], v[66:67], v[86:87]
	s_waitcnt vmcnt(2)
	v_pk_fma_f32 v[60:61], v[60:61], v[68:69], v[92:93]
	v_pk_fma_f32 v[58:59], v[58:59], v[66:67], v[90:91]
	s_waitcnt vmcnt(1)
	v_pk_fma_f32 v[56:57], v[56:57], v[68:69], v[96:97]
	v_pk_fma_f32 v[54:55], v[54:55], v[66:67], v[94:95]
	s_waitcnt vmcnt(0)
	v_pk_fma_f32 v[52:53], v[52:53], v[68:69], v[100:101]
	v_pk_fma_f32 v[50:51], v[50:51], v[66:67], v[98:99]
	global_store_dwordx4 v[136:137], v[46:49], off offset:512
	global_store_dwordx4 v[138:139], v[42:45], off offset:512
	global_store_dwordx4 v[140:141], v[38:41], off offset:512
	global_store_dwordx4 v[142:143], v[34:37], off offset:512
	global_store_dwordx4 v[144:145], v[62:65], off offset:512
	global_store_dwordx4 v[146:147], v[58:61], off offset:512
	global_store_dwordx4 v[150:151], v[54:57], off offset:512
	global_store_dwordx4 v[156:157], v[50:53], off offset:512
	global_load_dwordx4 v[34:37], v[148:149], off offset:576 nt
	global_load_dwordx4 v[38:41], v[152:153], off offset:576 nt
	global_load_dwordx4 v[42:45], v[154:155], off offset:576 nt
	global_load_dwordx4 v[46:49], v[158:159], off offset:576 nt
	s_nop 0
	global_load_dwordx4 v[50:53], v[160:161], off offset:576 nt
	global_load_dwordx4 v[54:57], v[162:163], off offset:576 nt
	global_load_dwordx4 v[58:61], v[164:165], off offset:576 nt
	global_load_dwordx4 v[62:65], v[166:167], off offset:576 nt
	global_load_dwordx4 v[66:69], v[168:169], off offset:576 nt
	s_waitcnt vmcnt(7)
	v_pk_fma_f32 v[4:5], v[4:5], v[36:37], v[40:41]
	v_pk_fma_f32 v[2:3], v[2:3], v[34:35], v[38:39]
	s_waitcnt vmcnt(6)
	v_pk_fma_f32 v[8:9], v[8:9], v[36:37], v[44:45]
	v_pk_fma_f32 v[6:7], v[6:7], v[34:35], v[42:43]
	s_waitcnt vmcnt(5)
	v_pk_fma_f32 v[12:13], v[12:13], v[36:37], v[48:49]
	v_pk_fma_f32 v[10:11], v[10:11], v[34:35], v[46:47]
	s_waitcnt vmcnt(4)
	v_pk_fma_f32 v[16:17], v[16:17], v[36:37], v[52:53]
	v_pk_fma_f32 v[14:15], v[14:15], v[34:35], v[50:51]
	s_waitcnt vmcnt(3)
	v_pk_fma_f32 v[20:21], v[20:21], v[36:37], v[56:57]
	v_pk_fma_f32 v[18:19], v[18:19], v[34:35], v[54:55]
	s_waitcnt vmcnt(2)
	v_pk_fma_f32 v[24:25], v[24:25], v[36:37], v[60:61]
	v_pk_fma_f32 v[22:23], v[22:23], v[34:35], v[58:59]
	s_waitcnt vmcnt(1)
	v_pk_fma_f32 v[28:29], v[28:29], v[36:37], v[64:65]
	v_pk_fma_f32 v[26:27], v[26:27], v[34:35], v[62:63]
	s_waitcnt vmcnt(0)
	v_pk_fma_f32 v[32:33], v[32:33], v[36:37], v[68:69]
	v_pk_fma_f32 v[30:31], v[30:31], v[34:35], v[66:67]
	global_store_dwordx4 v[136:137], v[2:5], off offset:576
	global_store_dwordx4 v[138:139], v[6:9], off offset:576
	global_store_dwordx4 v[140:141], v[10:13], off offset:576
	global_store_dwordx4 v[142:143], v[14:17], off offset:576
	global_store_dwordx4 v[144:145], v[18:21], off offset:576
	global_store_dwordx4 v[146:147], v[22:25], off offset:576
	global_store_dwordx4 v[150:151], v[26:29], off offset:576
	global_store_dwordx4 v[156:157], v[30:33], off offset:576
	s_cbranch_vccnz .LBB0_1251
	v_mov_b32_e32 v98, v1
	v_mov_b32_e32 v78, v1
	v_mov_b32_e32 v102, v1
	v_mov_b32_e32 v74, v1
	v_mov_b32_e32 v106, v1
	v_mov_b32_e32 v70, v1
	v_mov_b32_e32 v110, v1
	v_mov_b32_e32 v66, v1
	v_mov_b32_e32 v46, v1
	v_mov_b32_e32 v2, v1
	v_mov_b32_e32 v42, v1
	v_mov_b32_e32 v6, v1
	v_mov_b32_e32 v38, v1
	v_mov_b32_e32 v10, v1
	v_mov_b32_e32 v34, v1
	v_mov_b32_e32 v14, v1
	v_mov_b32_e32 v114, v1
	v_mov_b32_e32 v94, v1
	v_mov_b32_e32 v118, v1
	v_mov_b32_e32 v90, v1
	v_mov_b32_e32 v122, v1
	v_mov_b32_e32 v86, v1
	v_mov_b32_e32 v126, v1
	v_mov_b32_e32 v82, v1
	v_mov_b32_e32 v62, v1
	v_mov_b32_e32 v18, v1
	v_mov_b32_e32 v58, v1
	v_mov_b32_e32 v22, v1
	v_mov_b32_e32 v54, v1
	v_mov_b32_e32 v26, v1
	v_mov_b32_e32 v50, v1
	v_mov_b32_e32 v30, v1
	s_andn2_b64 vcc, exec, s[6:7]
	s_cbranch_vccnz .LBB0_1250
	s_barrier
	s_branch .LBB0_1250

;     __device__ __forceinline__ void operator()(const f32x4 (&acc)[2][2][4][2], const pg8::Unit& u, int wr, int wc, int fr, int fq) const {
;         const bool isc = u.pm == 64; const float* src = isc ? cin : hin; float* dst = isc ? cout : hout; const float* gv = isc ? gc : gl;
;         const int rbase = (isc ? 0 : u.pm * 256) + wr * 64 + fr, col0 = u.pn * 256 + wc * 32 + 4 * fq;
; #pragma unroll
;         for (int bj = 0; bj < 2; ++bj)
; #pragma unroll
;             for (int n = 0; n < 2; ++n) { const int col = col0 + bj * 128 + n * 16; const f32x4 g = *(const f32x4*)(gv + col); f32x4 h[2][4];
; #pragma unroll
;                 for (int ai = 0; ai < 2; ++ai)
; #pragma unroll
;                     for (int m = 0; m < 4; ++m) h[ai][m] = *(const f32x4*)(src + (size_t)(rbase + ai * 128 + m * 16) * DM + col);
; #pragma unroll
;                 for (int ai = 0; ai < 2; ++ai)
; #pragma unroll
;                     for (int m = 0; m < 4; ++m) *(f32x4*)(dst + (size_t)(rbase + ai * 128 + m * 16) * DM + col) = h[ai][m] + g * acc[ai][bj][m][n]; }
.LBB0_1596:
	s_lshl_b32 s40, s61, 8
	s_cmp_eq_u32 s61, 64
	s_mov_b32 s41, 0xa000
	s_cselect_b32 s41, 0x16000, s41
	s_cselect_b32 s42, 0, s40
	v_lshl_or_b32 v136, s60, 8, v148
	s_cselect_b32 s39, s52, s17
	s_cselect_b32 s38, s51, s16
	s_add_u32 s40, s53, s41
	v_add_u32_e32 v142, s42, v146
	v_ashrrev_i32_e32 v137, 31, v136
	s_addc_u32 s41, s54, 0
	v_lshlrev_b64 v[136:137], 2, v[136:137]
	v_ashrrev_i32_e32 v143, 31, v142
	v_lshl_add_u64 v[144:145], s[40:41], 0, v[136:137]
	v_lshl_add_u64 v[166:167], s[38:39], 0, v[136:137]
	v_lshlrev_b64 v[136:137], 13, v[142:143]
	v_lshl_add_u64 v[136:137], v[166:167], 0, v[136:137]
	s_mov_b32 s38, 0x100000
	v_add_co_u32_e32 v190, vcc, s38, v136
	v_or_b32_e32 v138, 16, v142
	s_nop 0
	v_addc_co_u32_e32 v191, vcc, 0, v137, vcc
	s_mov_b32 s38, 0x120000
	v_ashrrev_i32_e32 v139, 31, v138
	v_or_b32_e32 v140, 32, v142
	v_or_b32_e32 v142, 48, v142
	v_add_co_u32_e32 v192, vcc, s38, v136
	v_lshlrev_b64 v[138:139], 13, v[138:139]
	v_ashrrev_i32_e32 v141, 31, v140
	v_ashrrev_i32_e32 v143, 31, v142
	v_addc_co_u32_e32 v193, vcc, 0, v137, vcc
	s_mov_b32 s38, 0x140000
	global_load_dwordx4 v[150:153], v[144:145], off nt
	global_load_dwordx4 v[154:157], v[136:137], off nt
	v_lshl_add_u64 v[138:139], v[166:167], 0, v[138:139]
	v_lshlrev_b64 v[140:141], 13, v[140:141]
	v_lshlrev_b64 v[142:143], 13, v[142:143]
	v_add_co_u32_e32 v194, vcc, s38, v136
	global_load_dwordx4 v[158:161], v[138:139], off nt
	v_lshl_add_u64 v[140:141], v[166:167], 0, v[140:141]
	v_lshl_add_u64 v[142:143], v[166:167], 0, v[142:143]
	v_addc_co_u32_e32 v195, vcc, 0, v137, vcc
	s_mov_b32 s38, 0x160000
	global_load_dwordx4 v[162:165], v[140:141], off nt
	global_load_dwordx4 v[166:169], v[142:143], off nt
	global_load_dwordx4 v[170:173], v[190:191], off nt
	global_load_dwordx4 v[174:177], v[192:193], off nt
	v_add_co_u32_e32 v202, vcc, s38, v136
	global_load_dwordx4 v[178:181], v[194:195], off nt
	s_nop 0
	v_addc_co_u32_e32 v203, vcc, 0, v137, vcc
	global_load_dwordx4 v[182:185], v[202:203], off nt
	global_load_dwordx4 v[186:189], v[136:137], off offset:64 nt
	s_mov_b64 s[38:39], 0x100000
	s_and_b64 vcc, exec, s[4:5]
	s_mov_b64 s[4:5], -1
	s_movk_i32 s66, 0x2c00
	s_movk_i32 s62, 0x50
	s_mov_b32 s63, 0x8200
	s_movk_i32 s64, 0x63f
	s_movk_i32 s65, 0xdff
	s_waitcnt vmcnt(0)
	v_pk_fma_f32 v[100:101], v[100:101], v[152:153], v[156:157]
	v_pk_fma_f32 v[98:99], v[98:99], v[150:151], v[154:155]
	global_store_dwordx4 v[136:137], v[98:101], off
	s_nop 1
	v_pk_fma_f32 v[100:101], v[104:105], v[152:153], v[160:161]
	v_pk_fma_f32 v[98:99], v[102:103], v[150:151], v[158:159]
	v_pk_fma_f32 v[104:105], v[108:109], v[152:153], v[164:165]
	v_pk_fma_f32 v[102:103], v[106:107], v[150:151], v[162:163]
	v_pk_fma_f32 v[108:109], v[112:113], v[152:153], v[168:169]
	v_pk_fma_f32 v[106:107], v[110:111], v[150:151], v[166:167]
	global_store_dwordx4 v[138:139], v[98:101], off
	global_store_dwordx4 v[140:141], v[102:105], off
	global_store_dwordx4 v[142:143], v[106:109], off
	v_pk_fma_f32 v[100:101], v[116:117], v[152:153], v[172:173]
	v_pk_fma_f32 v[98:99], v[114:115], v[150:151], v[170:171]
	v_pk_fma_f32 v[104:105], v[120:121], v[152:153], v[176:177]
	v_pk_fma_f32 v[102:103], v[118:119], v[150:151], v[174:175]
	v_pk_fma_f32 v[108:109], v[124:125], v[152:153], v[180:181]
	v_pk_fma_f32 v[106:107], v[122:123], v[150:151], v[178:179]
	v_pk_fma_f32 v[112:113], v[128:129], v[152:153], v[184:185]
	v_pk_fma_f32 v[110:111], v[126:127], v[150:151], v[182:183]
	global_store_dwordx4 v[190:191], v[98:101], off
	global_store_dwordx4 v[192:193], v[102:105], off
	global_store_dwordx4 v[194:195], v[106:109], off
	global_store_dwordx4 v[202:203], v[110:113], off
	v_lshl_add_u64 v[98:99], v[136:137], 0, s[38:39]
	s_mov_b64 s[38:39], 0x120000
	v_lshl_add_u64 v[100:101], v[136:137], 0, s[38:39]
	s_mov_b64 s[38:39], 0x140000
	v_lshl_add_u64 v[102:103], v[136:137], 0, s[38:39]
	s_mov_b64 s[38:39], 0x160000
	global_load_dwordx4 v[106:109], v[144:145], off offset:64 nt
	global_load_dwordx4 v[110:113], v[138:139], off offset:64 nt
	global_load_dwordx4 v[114:117], v[140:141], off offset:64 nt
	global_load_dwordx4 v[118:121], v[142:143], off offset:64 nt
	global_load_dwordx4 v[122:125], v[98:99], off offset:64 nt
	global_load_dwordx4 v[126:129], v[100:101], off offset:64 nt
	global_load_dwordx4 v[150:153], v[102:103], off offset:64 nt
	v_lshl_add_u64 v[104:105], v[136:137], 0, s[38:39]
	global_load_dwordx4 v[154:157], v[104:105], off offset:64 nt
	global_load_dwordx4 v[158:161], v[136:137], off offset:512 nt
	s_waitcnt vmcnt(8)
	v_pk_fma_f32 v[36:37], v[36:37], v[108:109], v[188:189]
	v_pk_fma_f32 v[34:35], v[34:35], v[106:107], v[186:187]
	s_waitcnt vmcnt(7)
	v_pk_fma_f32 v[44:45], v[44:45], v[108:109], v[112:113]
	v_pk_fma_f32 v[42:43], v[42:43], v[106:107], v[110:111]
	s_waitcnt vmcnt(6)
	v_pk_fma_f32 v[52:53], v[52:53], v[108:109], v[116:117]
	v_pk_fma_f32 v[50:51], v[50:51], v[106:107], v[114:115]
	s_waitcnt vmcnt(5)
	v_pk_fma_f32 v[60:61], v[60:61], v[108:109], v[120:121]
	v_pk_fma_f32 v[58:59], v[58:59], v[106:107], v[118:119]
	s_waitcnt vmcnt(4)
	v_pk_fma_f32 v[68:69], v[68:69], v[108:109], v[124:125]
	v_pk_fma_f32 v[66:67], v[66:67], v[106:107], v[122:123]
	s_waitcnt vmcnt(3)
	v_pk_fma_f32 v[76:77], v[76:77], v[108:109], v[128:129]
	v_pk_fma_f32 v[74:75], v[74:75], v[106:107], v[126:127]
	s_waitcnt vmcnt(2)
	v_pk_fma_f32 v[84:85], v[84:85], v[108:109], v[152:153]
	v_pk_fma_f32 v[82:83], v[82:83], v[106:107], v[150:151]
	s_waitcnt vmcnt(1)
; #define PG8_BAR __builtin_amdgcn_s_barrier()
; template <class Epi, class Sched, bool ALIGN_EPI = false, bool SP2 = false>
; __device__ __forceinline__ void gemm_phase(PG8_LAS unsigned char* lds, const Gemm g, const Sched& S, const Epi& E) {
;     ...
; #pragma unroll
;         for (int a = 0; a < 2; ++a)
; #pragma unroll
;             for (int b = 0; b < 2; ++b)
; #pragma unroll
;                 for (int m = 0; m < 4; ++m)
; #pragma unroll
;                     for (int n = 0; n < 2; ++n) { float zr_ = 0.f; asm volatile("" : "+v"(zr_)); acc[a][b][m][n] = (f32x4){zr_, zr_, zr_, zr_}; }
;         cur = nxt; cA = nA; cB = nB; ++ui;
;         if constexpr (ALIGN_EPI) { if (wr == 1) PG8_BAR; }
;     __device__ __forceinline__ void operator()(const f32x4 (&acc)[2][2][4][2], const pg8::Unit& u, int wr, int wc, int fr, int fq) const {
;     ...
;             for (int n = 0; n < 2; ++n) { const int col = col0 + bj * 128 + n * 16; const f32x4 g = *(const f32x4*)(gv + col); f32x4 h[2][4];
; #pragma unroll
;                 for (int ai = 0; ai < 2; ++ai)
; #pragma unroll
;                     for (int m = 0; m < 4; ++m) h[ai][m] = *(const f32x4*)(src + (size_t)(rbase + ai * 128 + m * 16) * DM + col);
; #pragma unroll
;                 for (int ai = 0; ai < 2; ++ai)
; #pragma unroll
;                     for (int m = 0; m < 4; ++m) *(f32x4*)(dst + (size_t)(rbase + ai * 128 + m * 16) * DM + col) = h[ai][m] + g * acc[ai][bj][m][n]; }
	v_pk_fma_f32 v[92:93], v[92:93], v[108:109], v[156:157]
	v_pk_fma_f32 v[90:91], v[90:91], v[106:107], v[154:155]
	global_store_dwordx4 v[136:137], v[34:37], off offset:64
	global_store_dwordx4 v[138:139], v[42:45], off offset:64
	global_store_dwordx4 v[140:141], v[50:53], off offset:64
	global_store_dwordx4 v[142:143], v[58:61], off offset:64
	global_store_dwordx4 v[98:99], v[66:69], off offset:64
	global_store_dwordx4 v[100:101], v[74:77], off offset:64
	global_store_dwordx4 v[102:103], v[82:85], off offset:64
	global_store_dwordx4 v[104:105], v[90:93], off offset:64
	global_load_dwordx4 v[42:45], v[144:145], off offset:512 nt
	global_load_dwordx4 v[50:53], v[138:139], off offset:512 nt
	global_load_dwordx4 v[58:61], v[140:141], off offset:512 nt
	global_load_dwordx4 v[66:69], v[142:143], off offset:512 nt
	global_load_dwordx4 v[74:77], v[98:99], off offset:512 nt
	global_load_dwordx4 v[82:85], v[100:101], off offset:512 nt
	global_load_dwordx4 v[90:93], v[102:103], off offset:512 nt
	global_load_dwordx4 v[106:109], v[104:105], off offset:512 nt
	global_load_dwordx4 v[34:37], v[136:137], off offset:576 nt
	s_waitcnt vmcnt(8)
	v_pk_fma_f32 v[40:41], v[40:41], v[44:45], v[160:161]
	v_pk_fma_f32 v[38:39], v[38:39], v[42:43], v[158:159]
	s_waitcnt vmcnt(7)
	v_pk_fma_f32 v[48:49], v[48:49], v[44:45], v[52:53]
	v_pk_fma_f32 v[46:47], v[46:47], v[42:43], v[50:51]
	s_waitcnt vmcnt(6)
	v_pk_fma_f32 v[52:53], v[56:57], v[44:45], v[60:61]
	v_pk_fma_f32 v[50:51], v[54:55], v[42:43], v[58:59]
	s_waitcnt vmcnt(5)
	v_pk_fma_f32 v[56:57], v[64:65], v[44:45], v[68:69]
	v_pk_fma_f32 v[54:55], v[62:63], v[42:43], v[66:67]
	s_waitcnt vmcnt(4)
	v_pk_fma_f32 v[60:61], v[72:73], v[44:45], v[76:77]
	v_pk_fma_f32 v[58:59], v[70:71], v[42:43], v[74:75]
	s_waitcnt vmcnt(3)
	v_pk_fma_f32 v[64:65], v[80:81], v[44:45], v[84:85]
	v_pk_fma_f32 v[62:63], v[78:79], v[42:43], v[82:83]
	s_waitcnt vmcnt(2)
	v_pk_fma_f32 v[68:69], v[88:89], v[44:45], v[92:93]
	v_pk_fma_f32 v[66:67], v[86:87], v[42:43], v[90:91]
	s_waitcnt vmcnt(1)
	v_pk_fma_f32 v[44:45], v[96:97], v[44:45], v[108:109]
	v_pk_fma_f32 v[42:43], v[94:95], v[42:43], v[106:107]
	global_store_dwordx4 v[136:137], v[38:41], off offset:512
	global_store_dwordx4 v[138:139], v[46:49], off offset:512
	global_store_dwordx4 v[140:141], v[50:53], off offset:512
	global_store_dwordx4 v[142:143], v[54:57], off offset:512
	global_store_dwordx4 v[98:99], v[58:61], off offset:512
	global_store_dwordx4 v[100:101], v[62:65], off offset:512
	global_store_dwordx4 v[102:103], v[66:69], off offset:512
	global_store_dwordx4 v[104:105], v[42:45], off offset:512
	global_load_dwordx4 v[38:41], v[144:145], off offset:576 nt
	global_load_dwordx4 v[50:53], v[138:139], off offset:576 nt
	global_load_dwordx4 v[46:49], v[140:141], off offset:576 nt
	s_nop 0
	global_load_dwordx4 v[42:45], v[142:143], off offset:576 nt
	global_load_dwordx4 v[66:69], v[98:99], off offset:576 nt
	global_load_dwordx4 v[62:65], v[100:101], off offset:576 nt
	global_load_dwordx4 v[58:61], v[102:103], off offset:576 nt
	global_load_dwordx4 v[54:57], v[104:105], off offset:576 nt
	s_waitcnt vmcnt(7)
	v_pk_fma_f32 v[4:5], v[4:5], v[40:41], v[36:37]
	v_pk_fma_f32 v[2:3], v[2:3], v[38:39], v[34:35]
	s_waitcnt vmcnt(6)
	v_pk_fma_f32 v[8:9], v[8:9], v[40:41], v[52:53]
	v_pk_fma_f32 v[6:7], v[6:7], v[38:39], v[50:51]
	s_waitcnt vmcnt(5)
	v_pk_fma_f32 v[12:13], v[12:13], v[40:41], v[48:49]
	v_pk_fma_f32 v[10:11], v[10:11], v[38:39], v[46:47]
	s_waitcnt vmcnt(4)
	v_pk_fma_f32 v[16:17], v[16:17], v[40:41], v[44:45]
	v_pk_fma_f32 v[14:15], v[14:15], v[38:39], v[42:43]
	s_waitcnt vmcnt(3)
	v_pk_fma_f32 v[20:21], v[20:21], v[40:41], v[68:69]
	v_pk_fma_f32 v[18:19], v[18:19], v[38:39], v[66:67]
	s_waitcnt vmcnt(2)
	v_pk_fma_f32 v[24:25], v[24:25], v[40:41], v[64:65]
	v_pk_fma_f32 v[22:23], v[22:23], v[38:39], v[62:63]
	s_waitcnt vmcnt(1)
	v_pk_fma_f32 v[28:29], v[28:29], v[40:41], v[60:61]
	v_pk_fma_f32 v[26:27], v[26:27], v[38:39], v[58:59]
	s_waitcnt vmcnt(0)
	v_pk_fma_f32 v[32:33], v[32:33], v[40:41], v[56:57]
	v_pk_fma_f32 v[30:31], v[30:31], v[38:39], v[54:55]
	global_store_dwordx4 v[136:137], v[2:5], off offset:576
	global_store_dwordx4 v[138:139], v[6:9], off offset:576
	global_store_dwordx4 v[140:141], v[10:13], off offset:576
	global_store_dwordx4 v[142:143], v[14:17], off offset:576
	global_store_dwordx4 v[98:99], v[18:21], off offset:576
	global_store_dwordx4 v[100:101], v[22:25], off offset:576
	global_store_dwordx4 v[102:103], v[26:29], off offset:576
	global_store_dwordx4 v[104:105], v[30:33], off offset:576
	s_cbranch_vccnz .LBB0_1585
	v_mov_b32_e32 v98, v1
	v_mov_b32_e32 v34, v1
	v_mov_b32_e32 v102, v1
	v_mov_b32_e32 v42, v1
	v_mov_b32_e32 v106, v1
	v_mov_b32_e32 v50, v1
	v_mov_b32_e32 v110, v1
	v_mov_b32_e32 v58, v1
	v_mov_b32_e32 v38, v1
	v_mov_b32_e32 v2, v1
	v_mov_b32_e32 v46, v1
	v_mov_b32_e32 v6, v1
	v_mov_b32_e32 v54, v1
	v_mov_b32_e32 v10, v1
	v_mov_b32_e32 v62, v1
	v_mov_b32_e32 v14, v1
	v_mov_b32_e32 v114, v1
	v_mov_b32_e32 v66, v1
	v_mov_b32_e32 v118, v1
	v_mov_b32_e32 v74, v1
	v_mov_b32_e32 v122, v1
	v_mov_b32_e32 v82, v1
	v_mov_b32_e32 v126, v1
	v_mov_b32_e32 v90, v1
	v_mov_b32_e32 v70, v1
	v_mov_b32_e32 v18, v1
	v_mov_b32_e32 v78, v1
	v_mov_b32_e32 v22, v1
	v_mov_b32_e32 v86, v1
	v_mov_b32_e32 v26, v1
	v_mov_b32_e32 v94, v1
	v_mov_b32_e32 v30, v1
	s_andn2_b64 vcc, exec, s[14:15]
	s_cbranch_vccnz .LBB0_1584
	s_barrier
	s_branch .LBB0_1584
